# E45: grid barrier - all workgroups wait on the top arrival counter reaching its target (no separate release-generation hop)
# speedup vs baseline: 1.0255x; 1.0007x over previous
; DI unsigned xb_ld(unsigned* p)              { return __hip_atomic_load(p, __ATOMIC_RELAXED, __HIP_MEMORY_SCOPE_AGENT); }
; DI unsigned xb_add(unsigned* p, unsigned v) { return __hip_atomic_fetch_add(p, v, __ATOMIC_RELAXED, __HIP_MEMORY_SCOPE_AGENT); }
; #define XB_SPIN(cond, bar) do { unsigned _sp = 0; while (cond) { __builtin_amdgcn_s_sleep(1); \
;     if ((++_sp & 255u) == 0u) { if (xb_ld(&(bar)[XB_TMO])) break; if (_sp > XB_SPIN_CAP) { atomicAdd(&(bar)[XB_TMO], 1u); break; } } } } while (0)
; DI void xcd_barrier(const XcdBarrier& b) {
;     ...
;         const unsigned old = xb_add(&bar[XB_XSUB(b.x)], 1u);
;         const unsigned gen = old / nloc;
;         if (old + 1u == (gen + 1u) * nloc) {
;             __builtin_amdgcn_fence(__ATOMIC_RELEASE, "agent");
;             asm volatile("s_waitcnt vmcnt(0)" ::: "memory");
;             const unsigned og = xb_add(&bar[XB_TOP], 1u);
;             const unsigned tg = og / nx;
;             if (og + 1u == (tg + 1u) * nx) xb_add(&bar[XB_TOPGEN], 1u);
;             else XB_SPIN(xb_ld(&bar[XB_TOPGEN]) == tg, bar);
;             __builtin_amdgcn_fence(__ATOMIC_ACQUIRE, "agent");
;             xb_add(&bar[XB_XGEN(b.x)], 1u);
;             asm volatile("s_waitcnt vmcnt(0)" ::: "memory");
;         } else {
;             XB_SPIN(xb_ld(&bar[XB_XGEN(b.x)]) == gen, bar);
.LBB0_58:
	s_lshl_b32 s8, s3, 8
	s_add_u32 s8, s40, s8
	s_addc_u32 s9, s41, 0
	v_mov_b32_e32 v1, 0x1000
	v_mov_b32_e32 v3, 1
	global_atomic_add v3, v1, v3, s[8:9] offset:1024 sc0
	v_cvt_f32_u32_e32 v1, v2
	v_sub_u32_e32 v4, 0, v2
	s_add_u32 s8, s8, 0x2400
	s_addc_u32 s9, s9, 0
	v_rcp_iflag_f32_e32 v1, v1
	s_nop 0
	v_mul_f32_e32 v1, 0x4f7ffffe, v1
	v_cvt_u32_f32_e32 v1, v1
	v_mul_lo_u32 v4, v4, v1
	v_mul_hi_u32 v4, v1, v4
	v_add_u32_e32 v1, v1, v4
	s_waitcnt vmcnt(0)
	v_mul_hi_u32 v1, v3, v1
	v_mul_lo_u32 v4, v1, v2
	v_sub_u32_e32 v4, v3, v4
	v_add_u32_e32 v5, 1, v1
	v_cmp_ge_u32_e32 vcc, v4, v2
	v_add_u32_e32 v3, 1, v3
	s_nop 0
	v_cndmask_b32_e32 v1, v1, v5, vcc
	v_sub_u32_e32 v5, v4, v2
	v_cndmask_b32_e32 v4, v4, v5, vcc
	v_add_u32_e32 v5, 1, v1
	v_cmp_ge_u32_e32 vcc, v4, v2
	s_nop 1
	v_cndmask_b32_e32 v1, v1, v5, vcc
	v_mul_lo_u32 v4, v2, v1
	v_add_u32_e32 v2, v4, v2
	v_cmp_ne_u32_e32 vcc, v3, v2
	s_and_saveexec_b64 s[10:11], vcc
	s_xor_b64 s[10:11], exec, s[10:11]
	s_cbranch_execz .LBB0_72
	s_add_u32 s8, s6, 0x3200
	s_addc_u32 s9, s7, 0
	buffer_inv sc1
	s_waitcnt lgkmcnt(0)
	v_mad_u32_u24 v1, v1, v0, v0
	v_mov_b32_e32 v0, 0
	global_load_dword v2, v0, s[8:9] sc1
	s_waitcnt vmcnt(0)
	v_cmp_lt_u32_e32 vcc, v2, v1
	s_and_saveexec_b64 s[12:13], vcc
	s_cbranch_execz .LBB0_71
	s_mov_b32 s24, 1
	s_mov_b64 s[14:15], 0
	s_branch .LBB0_62

; DI unsigned xb_ld(unsigned* p)              { return __hip_atomic_load(p, __ATOMIC_RELAXED, __HIP_MEMORY_SCOPE_AGENT); }
; #define XB_SPIN(cond, bar) do { unsigned _sp = 0; while (cond) { __builtin_amdgcn_s_sleep(1); \
;     if ((++_sp & 255u) == 0u) { if (xb_ld(&(bar)[XB_TMO])) break; if (_sp > XB_SPIN_CAP) { atomicAdd(&(bar)[XB_TMO], 1u); break; } } } } while (0)
; DI void xcd_barrier(const XcdBarrier& b) {
;     ...
;             XB_SPIN(xb_ld(&bar[XB_XGEN(b.x)]) == gen, bar);
.LBB0_64:
	global_load_dword v2, v0, s[8:9] sc1
	s_add_i32 s24, s24, 1
	s_mov_b64 s[20:21], -1
	s_waitcnt vmcnt(0)
	v_cmp_ge_u32_e32 vcc, v2, v1
	s_orn2_b64 s[18:19], vcc, exec
	s_branch .LBB0_61

; DI unsigned xb_ld(unsigned* p)              { return __hip_atomic_load(p, __ATOMIC_RELAXED, __HIP_MEMORY_SCOPE_AGENT); }
; DI unsigned xb_add(unsigned* p, unsigned v) { return __hip_atomic_fetch_add(p, v, __ATOMIC_RELAXED, __HIP_MEMORY_SCOPE_AGENT); }
; #define XB_SPIN(cond, bar) do { unsigned _sp = 0; while (cond) { __builtin_amdgcn_s_sleep(1); \
;     if ((++_sp & 255u) == 0u) { if (xb_ld(&(bar)[XB_TMO])) break; if (_sp > XB_SPIN_CAP) { atomicAdd(&(bar)[XB_TMO], 1u); break; } } } } while (0)
; DI void xcd_barrier(const XcdBarrier& b) {
;     ...
;             const unsigned og = xb_add(&bar[XB_TOP], 1u);
;             const unsigned tg = og / nx;
;             if (og + 1u == (tg + 1u) * nx) xb_add(&bar[XB_TOPGEN], 1u);
;             else XB_SPIN(xb_ld(&bar[XB_TOPGEN]) == tg, bar);
.LBB0_75:
	s_or_b64 exec, exec, s[12:13]
	v_cvt_f32_u32_e32 v3, v0
	s_waitcnt vmcnt(0)
	v_readfirstlane_b32 s12, v2
	s_add_u32 s10, s36, 0x7500
	s_addc_u32 s11, s37, 0
	v_rcp_iflag_f32_e32 v3, v3
	v_add_u32_e32 v1, s12, v1
	s_mov_b64 s[14:15], -1
	v_mul_f32_e32 v2, 0x4f7ffffe, v3
	v_cvt_u32_f32_e32 v2, v2
	v_sub_u32_e32 v3, 0, v0
	v_mul_lo_u32 v3, v3, v2
	v_mul_hi_u32 v3, v2, v3
	v_add_u32_e32 v2, v2, v3
	v_mul_hi_u32 v2, v1, v2
	v_mul_lo_u32 v3, v2, v0
	v_sub_u32_e32 v3, v1, v3
	v_add_u32_e32 v4, 1, v2
	v_cmp_ge_u32_e32 vcc, v3, v0
	v_add_u32_e32 v1, 1, v1
	s_nop 0
	v_cndmask_b32_e32 v2, v2, v4, vcc
	v_sub_u32_e32 v4, v3, v0
	v_cndmask_b32_e32 v3, v3, v4, vcc
	v_add_u32_e32 v4, 1, v2
	v_cmp_ge_u32_e32 vcc, v3, v0
	s_nop 1
	v_cndmask_b32_e32 v2, v2, v4, vcc
	v_mul_lo_u32 v3, v0, v2
	v_add_u32_e32 v0, v3, v0
	v_cmp_ne_u32_e32 vcc, v1, v0
	v_mov_b32_e32 v2, v0
	v_mov_b64_e32 v[0:1], s[10:11]
	s_and_saveexec_b64 s[12:13], vcc
	s_cbranch_execz .LBB0_87
	s_sub_u32 s10, s10, 0x100
	s_subb_u32 s11, s11, 0
	v_mov_b32_e32 v0, 0
	global_load_dword v1, v0, s[10:11] sc1
	s_mov_b64 s[16:17], 0
	s_waitcnt vmcnt(0)
	v_cmp_lt_u32_e32 vcc, v1, v2
	s_and_saveexec_b64 s[14:15], vcc
	s_cbranch_execz .LBB0_86
	s_mov_b32 s26, 1
	s_branch .LBB0_79

; DI unsigned xb_ld(unsigned* p)              { return __hip_atomic_load(p, __ATOMIC_RELAXED, __HIP_MEMORY_SCOPE_AGENT); }
; #define XB_SPIN(cond, bar) do { unsigned _sp = 0; while (cond) { __builtin_amdgcn_s_sleep(1); \
;     if ((++_sp & 255u) == 0u) { if (xb_ld(&(bar)[XB_TMO])) break; if (_sp > XB_SPIN_CAP) { atomicAdd(&(bar)[XB_TMO], 1u); break; } } } } while (0)
; DI void xcd_barrier(const XcdBarrier& b) {
;     ...
;             else XB_SPIN(xb_ld(&bar[XB_TOPGEN]) == tg, bar);
.LBB0_81:
	global_load_dword v1, v0, s[10:11] sc1
	s_add_i32 s26, s26, 1
	s_mov_b64 s[20:21], -1
	s_waitcnt vmcnt(0)
	v_cmp_ge_u32_e32 vcc, v1, v2
	s_orn2_b64 s[24:25], vcc, exec
	s_branch .LBB0_78

; DI unsigned xb_ld(unsigned* p)              { return __hip_atomic_load(p, __ATOMIC_RELAXED, __HIP_MEMORY_SCOPE_AGENT); }
; DI unsigned xb_add(unsigned* p, unsigned v) { return __hip_atomic_fetch_add(p, v, __ATOMIC_RELAXED, __HIP_MEMORY_SCOPE_AGENT); }
; #define XB_SPIN(cond, bar) do { unsigned _sp = 0; while (cond) { __builtin_amdgcn_s_sleep(1); \
;     if ((++_sp & 255u) == 0u) { if (xb_ld(&(bar)[XB_TMO])) break; if (_sp > XB_SPIN_CAP) { atomicAdd(&(bar)[XB_TMO], 1u); break; } } } } while (0)
; DI void xcd_barrier(const XcdBarrier& b) {
;     ...
;         const unsigned old = xb_add(&bar[XB_XSUB(b.x)], 1u);
;         const unsigned gen = old / nloc;
;         if (old + 1u == (gen + 1u) * nloc) {
;             __builtin_amdgcn_fence(__ATOMIC_RELEASE, "agent");
;             asm volatile("s_waitcnt vmcnt(0)" ::: "memory");
;             const unsigned og = xb_add(&bar[XB_TOP], 1u);
;             const unsigned tg = og / nx;
;             if (og + 1u == (tg + 1u) * nx) xb_add(&bar[XB_TOPGEN], 1u);
;             else XB_SPIN(xb_ld(&bar[XB_TOPGEN]) == tg, bar);
;             __builtin_amdgcn_fence(__ATOMIC_ACQUIRE, "agent");
;             xb_add(&bar[XB_XGEN(b.x)], 1u);
;             asm volatile("s_waitcnt vmcnt(0)" ::: "memory");
;         } else {
;             XB_SPIN(xb_ld(&bar[XB_XGEN(b.x)]) == gen, bar);
.LBB0_1005:
	v_readlane_b32 s4, v253, 52
	v_readlane_b32 s5, v253, 53
	v_cvt_f32_u32_e32 v1, v2
	v_sub_u32_e32 v4, 0, v2
	v_rcp_iflag_f32_e32 v1, v1
	s_nop 1
	global_atomic_add v3, v173, v237, s[4:5] sc0
	v_mul_f32_e32 v1, 0x4f7ffffe, v1
	v_cvt_u32_f32_e32 v1, v1
	v_mul_lo_u32 v4, v4, v1
	v_mul_hi_u32 v4, v1, v4
	v_add_u32_e32 v1, v1, v4
	s_waitcnt vmcnt(0)
	v_mul_hi_u32 v1, v3, v1
	v_mul_lo_u32 v4, v1, v2
	v_sub_u32_e32 v4, v3, v4
	v_add_u32_e32 v5, 1, v1
	v_cmp_ge_u32_e32 vcc, v4, v2
	v_add_u32_e32 v3, 1, v3
	s_nop 0
	v_cndmask_b32_e32 v1, v1, v5, vcc
	v_sub_u32_e32 v5, v4, v2
	v_cndmask_b32_e32 v4, v4, v5, vcc
	v_add_u32_e32 v5, 1, v1
	v_cmp_ge_u32_e32 vcc, v4, v2
	s_nop 1
	v_cndmask_b32_e32 v1, v1, v5, vcc
	v_mul_lo_u32 v4, v2, v1
	v_add_u32_e32 v2, v4, v2
	v_cmp_ne_u32_e32 vcc, v3, v2
	s_and_saveexec_b64 s[4:5], vcc
	s_xor_b64 s[4:5], exec, s[4:5]
	s_cbranch_execz .LBB0_1019
	s_add_u32 s6, s62, 0x3200
	s_addc_u32 s7, s63, 0
	buffer_inv sc1
	s_waitcnt lgkmcnt(0)
	v_mad_u32_u24 v1, v1, v0, v0
	s_nop 3
	global_load_dword v0, v173, s[6:7] sc1
	s_waitcnt vmcnt(0)
	v_cmp_lt_u32_e32 vcc, v0, v1
	s_and_saveexec_b64 s[6:7], vcc
	s_cbranch_execz .LBB0_1018
	s_mov_b32 s18, 1
	s_mov_b64 s[8:9], 0
	s_branch .LBB0_1009

; DI unsigned xb_ld(unsigned* p)              { return __hip_atomic_load(p, __ATOMIC_RELAXED, __HIP_MEMORY_SCOPE_AGENT); }
; #define XB_SPIN(cond, bar) do { unsigned _sp = 0; while (cond) { __builtin_amdgcn_s_sleep(1); \
;     if ((++_sp & 255u) == 0u) { if (xb_ld(&(bar)[XB_TMO])) break; if (_sp > XB_SPIN_CAP) { atomicAdd(&(bar)[XB_TMO], 1u); break; } } } } while (0)
; DI void xcd_barrier(const XcdBarrier& b) {
;     ...
;             XB_SPIN(xb_ld(&bar[XB_XGEN(b.x)]) == gen, bar);
.LBB0_1011:
	s_add_u32 s12, s62, 0x3200
	s_addc_u32 s13, s63, 0
	s_add_i32 s18, s18, 1
	s_mov_b64 s[14:15], -1
	s_nop 2
	global_load_dword v0, v173, s[12:13] sc1
	s_waitcnt vmcnt(0)
	v_cmp_ge_u32_e32 vcc, v0, v1
	s_orn2_b64 s[12:13], vcc, exec
	s_branch .LBB0_1008

; DI unsigned xb_ld(unsigned* p)              { return __hip_atomic_load(p, __ATOMIC_RELAXED, __HIP_MEMORY_SCOPE_AGENT); }
; DI unsigned xb_add(unsigned* p, unsigned v) { return __hip_atomic_fetch_add(p, v, __ATOMIC_RELAXED, __HIP_MEMORY_SCOPE_AGENT); }
; #define XB_SPIN(cond, bar) do { unsigned _sp = 0; while (cond) { __builtin_amdgcn_s_sleep(1); \
;     if ((++_sp & 255u) == 0u) { if (xb_ld(&(bar)[XB_TMO])) break; if (_sp > XB_SPIN_CAP) { atomicAdd(&(bar)[XB_TMO], 1u); break; } } } } while (0)
; DI void xcd_barrier(const XcdBarrier& b) {
;     ...
;         const unsigned old = xb_add(&bar[XB_XSUB(b.x)], 1u);
;         const unsigned gen = old / nloc;
;         if (old + 1u == (gen + 1u) * nloc) {
;             __builtin_amdgcn_fence(__ATOMIC_RELEASE, "agent");
;             asm volatile("s_waitcnt vmcnt(0)" ::: "memory");
;             const unsigned og = xb_add(&bar[XB_TOP], 1u);
;             const unsigned tg = og / nx;
;             if (og + 1u == (tg + 1u) * nx) xb_add(&bar[XB_TOPGEN], 1u);
;             else XB_SPIN(xb_ld(&bar[XB_TOPGEN]) == tg, bar);
.LBB0_1022:
	s_or_b64 exec, exec, s[6:7]
	s_waitcnt vmcnt(0)
	v_readfirstlane_b32 s4, v2
	v_cvt_f32_u32_e32 v2, v0
	v_sub_u32_e32 v3, 0, v0
	v_add_u32_e32 v1, s4, v1
	v_readlane_b32 s4, v253, 58
	v_rcp_iflag_f32_e32 v2, v2
	v_readlane_b32 s5, v253, 59
	s_mov_b64 s[6:7], -1
	v_mul_f32_e32 v2, 0x4f7ffffe, v2
	v_cvt_u32_f32_e32 v2, v2
	v_mul_lo_u32 v3, v3, v2
	v_mul_hi_u32 v3, v2, v3
	v_add_u32_e32 v2, v2, v3
	v_mul_hi_u32 v2, v1, v2
	v_mul_lo_u32 v3, v2, v0
	v_sub_u32_e32 v3, v1, v3
	v_cmp_ge_u32_e32 vcc, v3, v0
	v_add_u32_e32 v4, 1, v2
	v_add_u32_e32 v1, 1, v1
	v_cndmask_b32_e32 v2, v2, v4, vcc
	v_sub_u32_e32 v4, v3, v0
	v_cndmask_b32_e32 v3, v3, v4, vcc
	v_cmp_ge_u32_e32 vcc, v3, v0
	v_add_u32_e32 v3, 1, v2
	s_nop 0
	v_cndmask_b32_e32 v2, v2, v3, vcc
	v_mul_lo_u32 v3, v0, v2
	v_add_u32_e32 v0, v3, v0
	v_cmp_ne_u32_e32 vcc, v1, v0
	v_mov_b32_e32 v2, v0
	v_mov_b64_e32 v[0:1], s[4:5]
	s_and_saveexec_b64 s[4:5], vcc
	s_cbranch_execz .LBB0_1034
	v_readlane_b32 s6, v253, 56
	v_readlane_b32 s7, v253, 57
	s_mov_b64 s[8:9], 0
	s_nop 3
	global_load_dword v0, v173, s[6:7] sc1
	s_waitcnt vmcnt(0)
	v_cmp_lt_u32_e32 vcc, v0, v2
	s_and_saveexec_b64 s[6:7], vcc
	s_cbranch_execz .LBB0_1033
	s_mov_b32 s18, 1
	s_branch .LBB0_1026

; DI unsigned xb_ld(unsigned* p)              { return __hip_atomic_load(p, __ATOMIC_RELAXED, __HIP_MEMORY_SCOPE_AGENT); }
; #define XB_SPIN(cond, bar) do { unsigned _sp = 0; while (cond) { __builtin_amdgcn_s_sleep(1); \
;     if ((++_sp & 255u) == 0u) { if (xb_ld(&(bar)[XB_TMO])) break; if (_sp > XB_SPIN_CAP) { atomicAdd(&(bar)[XB_TMO], 1u); break; } } } } while (0)
; DI void xcd_barrier(const XcdBarrier& b) {
;     ...
;             else XB_SPIN(xb_ld(&bar[XB_TOPGEN]) == tg, bar);
.LBB0_1028:
	v_readlane_b32 s12, v253, 56
	v_readlane_b32 s13, v253, 57
	s_add_i32 s18, s18, 1
	s_mov_b64 s[14:15], -1
	s_nop 2
	global_load_dword v0, v173, s[12:13] sc1
	s_waitcnt vmcnt(0)
	v_cmp_ge_u32_e32 vcc, v0, v2
	s_orn2_b64 s[12:13], vcc, exec
	s_branch .LBB0_1025
